# v58 + RCX: retention contrib unit takes its decay logits from a per-phase scalar load and waits for the K/V prefetch with vmcnt(16) (no wait behind the previous unit's state stores)
# speedup vs baseline: 1.0048x; 1.0048x over previous
; __device__ __forceinline__ float log_sigmoid(float x) { return fminf(x, 0.f) - log1pf(expf(-fabsf(x))); }
; __device__ __forceinline__ void ret_contrib_unit(int unit, int next_unit, RetKV& pre, const bf16* RK, const bf16* RV, const float* decay_l, float* RETC, lds_t* lds, int tid, int lane, int wave) {
;     const int c = unit % 34, bh = unit / 34, h = bh & 3, b = bh >> 2;
;     lds_t* Kft = lds; lds_t* Kbt = lds + 64 * RT_LDK; lds_t* Vt = lds + 128 * RT_LDK;
;     const float lgf = log_sigmoid(decay_l[h]), lgb = log_sigmoid(decay_l[4 + h]);
;     { const int j = tid >> 2, d0 = (tid & 3) * 16; const float wf = __expf(lgf * (float)(127 - j)), wb = __expf(lgb * (float)j);
.LBB0_540:
	s_lshl_b32 s84, s26, 3
	v_readlane_b32 s16, v252, 8
	v_readlane_b32 s26, v252, 18
	v_readlane_b32 s27, v252, 19
	v_readlane_b32 s30, v252, 22
	v_readlane_b32 s31, v252, 23
	s_lshl_b64 s[10:11], s[84:85], 2
	s_mov_b64 s[26:27], s[30:31]
	s_add_u32 s82, s26, s10
	s_movk_i32 s34, 0xff
	s_addc_u32 s83, s27, s11
	s_andn2_b64 vcc, exec, s[8:9]
	v_readlane_b32 s17, v252, 9
	v_readlane_b32 s18, v252, 10
	v_readlane_b32 s19, v252, 11
	v_readlane_b32 s20, v252, 12
	v_readlane_b32 s21, v252, 13
	v_readlane_b32 s22, v252, 14
	v_readlane_b32 s23, v252, 15
	v_readlane_b32 s24, v252, 16
	v_readlane_b32 s25, v252, 17
	v_readlane_b32 s28, v252, 20
	v_readlane_b32 s29, v252, 21
	s_cbranch_vccnz .LBB0_549
	s_ashr_i32 s7, s1, 6
	s_ashr_i32 s8, s1, 8
	s_cmp_lt_u32 s7, 4
	v_readlane_b32 s1, v255, 48
	s_cselect_b32 s1, 0, s1
	s_lshl_b32 s9, s7, 4
	s_and_b32 s10, s9, 32
	s_mul_i32 s9, s10, 0x110
	v_ashrrev_i32_e32 v19, 2, v0
	v_lshlrev_b32_e32 v2, 4, v0
	s_add_i32 s1, s1, s9
	s_lshl_b32 s9, s7, 5
	v_and_b32_e32 v18, 48, v2
	v_sub_u32_e32 v2, 0x7f, v19
	s_and_b32 s12, s9, 32
	v_cvt_f32_i32_e32 v30, v2
	s_mul_i32 s9, s12, 0x110
	v_and_b32_e32 v2, 31, v0
	v_mov_b32_e32 v3, s1
	s_movk_i32 s1, 0x110
	s_add_i32 s9, s9, 0
	v_mad_u32_u24 v6, v2, s1, v3
	v_lshrrev_b32_e32 v3, 1, v0
	v_and_b32_e32 v7, 16, v3
	v_mov_b32_e32 v3, s9
	v_mad_u32_u24 v8, v2, s1, v3
	s_ashr_i32 s9, s8, 31
	v_lshrrev_b32_e32 v3, 3, v0
	s_lshl_b32 s1, s7, 12
	v_lshlrev_b32_e32 v0, 5, v0
	s_ashr_i32 s7, s6, 31
	s_lshl_b64 s[8:9], s[8:9], 14
	v_and_or_b32 v3, v3, 7, s10
	s_and_b32 s1, s1, 0x2000
	v_and_b32_e32 v0, 0x400, v0
	s_lshl_b64 s[10:11], s[6:7], 15
	v_or_b32_e32 v0, s1, v0
	s_add_u32 s1, s10, s8
	v_cvt_f32_i32_e32 v31, v19
	s_addc_u32 s7, s11, s9
	v_or_b32_e32 v2, s12, v2
	s_add_u32 s8, s94, s1
	v_lshl_add_u32 v4, v19, 1, 0
	v_mul_u32_u24_e32 v5, 0x110, v18
	v_lshlrev_b32_e32 v9, 8, v3
	v_lshlrev_b32_e32 v2, 2, v2
	v_mov_b32_e32 v3, v1
	s_addc_u32 s9, s95, s7
	s_ashr_i32 s1, s0, 31
	v_lshl_add_u64 v[20:21], s[8:9], 0, v[2:3]
	s_lshl_b64 s[8:9], s[0:1], 15
	v_or_b32_e32 v22, 0x6801b00, v9
	v_mov_b32_e32 v23, v1
	v_or_b32_e32 v24, 0x6801300, v9
	v_mov_b32_e32 v25, v1
	v_or_b32_e32 v26, 0x6800b00, v9
	v_mov_b32_e32 v27, v1
	v_or_b32_e32 v28, 0x6800300, v9
	v_mov_b32_e32 v29, v1
	v_add_u32_e32 v32, v4, v5
	v_add_u32_e32 v33, v6, v7
	v_add_u32_e32 v34, v8, v7
	s_load_dwordx8 s[24:31], s[82:83], 0x0
	s_waitcnt vmcnt(0) lgkmcnt(0)
	s_branch .LBB0_544

; __device__ __forceinline__ float log_sigmoid(float x) { return fminf(x, 0.f) - log1pf(expf(-fabsf(x))); }
; __device__ __forceinline__ void ret_contrib_unit(int unit, int next_unit, RetKV& pre, const bf16* RK, const bf16* RV, const float* decay_l, float* RETC, lds_t* lds, int tid, int lane, int wave) {
;     const int c = unit % 34, bh = unit / 34, h = bh & 3, b = bh >> 2;
;     lds_t* Kft = lds; lds_t* Kbt = lds + 64 * RT_LDK; lds_t* Vt = lds + 128 * RT_LDK;
;     const float lgf = log_sigmoid(decay_l[h]), lgb = log_sigmoid(decay_l[4 + h]);
.LBB0_544:
	s_mov_b32 s7, s6
	s_add_i32 s6, s6, s0
	s_cmp_ge_i32 s6, s14
	s_cselect_b64 s[10:11], -1, 0
	s_cmp_lt_i32 s6, s14
	s_mul_hi_i32 s7, s7, 0x78787879
	s_cselect_b32 s1, s6, -1
	s_lshr_b32 s12, s7, 31
	s_lshr_b32 s7, s7, 4
	s_add_i32 s7, s7, s12
	s_and_b32 s7, s7, 3
	s_lshl_b32 s7, s7, 2
	s_cmp_lt_u32 s7, 8
	s_cselect_b32 s18, s24, s26
	s_cselect_b32 s19, s25, s27
	s_cselect_b32 s20, s28, s30
	s_cselect_b32 s21, s29, s31
	s_bitcmp1_b32 s7, 2
	s_cselect_b32 s18, s19, s18
	s_cselect_b32 s20, s21, s20
	v_mov_b32_e32 v3, s18
	v_mov_b32_e32 v2, s20
	s_cmp_lt_i32 s1, 0
	v_max_f32_e32 v4, v3, v3
	v_min_f32_e32 v6, 0, v4
	v_mul_f32_e64 v4, |v3|, s35
	v_fma_f32 v5, |v3|, s35, -v4
	v_rndne_f32_e32 v7, v4
	v_fma_f32 v5, |v3|, s37, v5
	v_sub_f32_e32 v4, v4, v7
	v_add_f32_e32 v4, v4, v5
	v_exp_f32_e32 v4, v4
	v_cvt_i32_f32_e32 v5, v7
	v_cmp_ngt_f32_e64 vcc, |v3|, s38
	v_ldexp_f32 v4, v4, v5
	s_nop 0
	v_cndmask_b32_e32 v4, 0, v4, vcc
	v_cmp_nlt_f32_e64 vcc, |v3|, s39
	s_nop 1
	v_cndmask_b32_e32 v3, v219, v4, vcc
	v_add_f32_e32 v7, 1.0, v3
	v_add_f32_e32 v4, -1.0, v7
	v_sub_f32_e32 v5, v4, v7
	v_add_f32_e32 v5, 1.0, v5
	v_sub_f32_e32 v4, v3, v4
	v_add_f32_e32 v8, v4, v5
	v_frexp_mant_f32_e32 v4, v7
	v_cmp_gt_f32_e32 vcc, s48, v4
	v_cvt_f64_f32_e32 v[4:5], v7
	v_frexp_exp_i32_f64_e32 v4, v[4:5]
	v_subbrev_co_u32_e32 v4, vcc, 0, v4, vcc
	v_sub_u32_e32 v5, 0, v4
	v_ldexp_f32 v7, v7, v5
	v_ldexp_f32 v5, v8, v5
	v_add_f32_e32 v8, -1.0, v7
	v_add_f32_e32 v9, 1.0, v8
	v_sub_f32_e32 v9, v7, v9
	v_add_f32_e32 v9, v5, v9
	v_add_f32_e32 v10, v8, v9
	v_sub_f32_e32 v8, v8, v10
	v_add_f32_e32 v8, v9, v8
	v_add_f32_e32 v9, 1.0, v7
	v_add_f32_e32 v11, -1.0, v9
	v_sub_f32_e32 v7, v7, v11
	v_add_f32_e32 v5, v5, v7
	v_add_f32_e32 v7, v9, v5
	v_sub_f32_e32 v9, v9, v7
	v_add_f32_e32 v5, v5, v9
	v_rcp_f32_e32 v9, v7
	v_cvt_f32_i32_e32 v4, v4
	v_cmp_neq_f32_e32 vcc, s46, v3
	v_mul_f32_e32 v11, v10, v9
	v_mul_f32_e32 v12, v7, v11
	v_fma_f32 v13, v11, v7, -v12
	v_fmac_f32_e32 v13, v11, v5
	v_add_f32_e32 v14, v12, v13
	v_sub_f32_e32 v15, v10, v14
	v_sub_f32_e32 v10, v10, v15
	v_sub_f32_e32 v12, v14, v12
	v_sub_f32_e32 v10, v10, v14
	v_add_f32_e32 v8, v8, v10
	v_sub_f32_e32 v10, v12, v13
	v_add_f32_e32 v8, v10, v8
	v_add_f32_e32 v10, v15, v8
	v_mul_f32_e32 v12, v9, v10
	v_mul_f32_e32 v13, v7, v12
	v_fma_f32 v7, v12, v7, -v13
	v_fmac_f32_e32 v7, v12, v5
	v_sub_f32_e32 v5, v15, v10
	v_add_f32_e32 v5, v8, v5
	v_add_f32_e32 v8, v13, v7
	v_sub_f32_e32 v14, v10, v8
	v_sub_f32_e32 v10, v10, v14
	v_sub_f32_e32 v13, v8, v13
	v_sub_f32_e32 v8, v10, v8
	v_add_f32_e32 v5, v5, v8
	v_sub_f32_e32 v7, v13, v7
	v_add_f32_e32 v5, v7, v5
	v_add_f32_e32 v7, v11, v12
	v_add_f32_e32 v5, v14, v5
	v_sub_f32_e32 v8, v7, v11
	v_mul_f32_e32 v5, v9, v5
	v_sub_f32_e32 v8, v12, v8
	v_add_f32_e32 v5, v8, v5
	v_mul_f32_e32 v11, 0x3f317218, v4
	v_add_f32_e32 v8, v7, v5
	v_fma_f32 v12, v4, s49, -v11
	v_mul_f32_e32 v9, v8, v8
	v_fmac_f32_e32 v12, 0xb102e308, v4
	v_sub_f32_e32 v4, v8, v7
	v_fmamk_f32 v10, v9, 0x3e9b6dac, v217
	v_sub_f32_e32 v4, v5, v4
	v_add_f32_e32 v5, v11, v12
	v_fmaak_f32 v10, v9, v10, 0x3f2aaada
	v_sub_f32_e32 v7, v5, v11
	v_ldexp_f32 v11, v8, 1
	v_mul_f32_e32 v8, v8, v9
	v_mul_f32_e32 v8, v8, v10
	v_add_f32_e32 v9, v11, v8
	v_sub_f32_e32 v10, v9, v11
	v_ldexp_f32 v4, v4, 1
	v_sub_f32_e32 v8, v8, v10
	v_add_f32_e32 v4, v4, v8
	v_add_f32_e32 v8, v9, v4
	v_sub_f32_e32 v9, v8, v9
	v_sub_f32_e32 v4, v4, v9
	v_add_f32_e32 v9, v5, v8
	v_sub_f32_e32 v10, v9, v5
	v_sub_f32_e32 v11, v9, v10
	v_sub_f32_e32 v7, v12, v7
	v_sub_f32_e32 v5, v5, v11
	v_sub_f32_e32 v8, v8, v10
	v_add_f32_e32 v5, v8, v5
	v_add_f32_e32 v8, v7, v4
	v_sub_f32_e32 v10, v8, v7
	v_sub_f32_e32 v11, v8, v10
	v_sub_f32_e32 v7, v7, v11
	v_sub_f32_e32 v4, v4, v10
	v_add_f32_e32 v5, v8, v5
	v_add_f32_e32 v4, v4, v7
	v_add_f32_e32 v7, v9, v5
	v_sub_f32_e32 v8, v7, v9
	v_sub_f32_e32 v5, v5, v8
	v_add_f32_e32 v4, v4, v5
	v_add_f32_e32 v4, v7, v4
	v_cndmask_b32_e32 v4, v219, v4, vcc
	v_cmp_lt_f32_e64 vcc, |v3|, s50
	s_nop 1
	v_cndmask_b32_e32 v3, v4, v3, vcc
	v_sub_f32_e32 v4, v6, v3
	v_max_f32_e32 v3, v2, v2
	v_min_f32_e32 v5, 0, v3
	v_mul_f32_e64 v3, |v2|, s35
	v_fma_f32 v6, |v2|, s35, -v3
	v_rndne_f32_e32 v7, v3
	v_fma_f32 v6, |v2|, s37, v6
	v_sub_f32_e32 v3, v3, v7
	v_add_f32_e32 v3, v3, v6
	v_exp_f32_e32 v3, v3
	v_cvt_i32_f32_e32 v6, v7
	v_cmp_ngt_f32_e64 vcc, |v2|, s38
	v_ldexp_f32 v3, v3, v6
	s_nop 0
	v_cndmask_b32_e32 v3, 0, v3, vcc
	v_cmp_nlt_f32_e64 vcc, |v2|, s39
	s_nop 1
	v_cndmask_b32_e32 v6, v219, v3, vcc
	v_add_f32_e32 v7, 1.0, v6
	v_add_f32_e32 v2, -1.0, v7
	v_sub_f32_e32 v3, v2, v7
	v_add_f32_e32 v3, 1.0, v3
	v_sub_f32_e32 v2, v6, v2
	v_add_f32_e32 v8, v2, v3
	v_frexp_mant_f32_e32 v2, v7
	v_cmp_gt_f32_e32 vcc, s48, v2
	v_cvt_f64_f32_e32 v[2:3], v7
	v_frexp_exp_i32_f64_e32 v2, v[2:3]
	v_subbrev_co_u32_e32 v2, vcc, 0, v2, vcc
	v_sub_u32_e32 v3, 0, v2
	v_ldexp_f32 v7, v7, v3
	v_ldexp_f32 v3, v8, v3
	v_add_f32_e32 v8, -1.0, v7
	v_add_f32_e32 v9, 1.0, v8
	v_sub_f32_e32 v9, v7, v9
	v_add_f32_e32 v9, v3, v9
	v_add_f32_e32 v10, v8, v9
	v_sub_f32_e32 v8, v8, v10
	v_add_f32_e32 v8, v9, v8
	v_add_f32_e32 v9, 1.0, v7
	v_add_f32_e32 v11, -1.0, v9
	v_sub_f32_e32 v7, v7, v11
	v_add_f32_e32 v3, v3, v7
	v_add_f32_e32 v7, v9, v3
	v_sub_f32_e32 v9, v9, v7
	v_add_f32_e32 v3, v3, v9
	v_rcp_f32_e32 v9, v7
	v_cvt_f32_i32_e32 v2, v2
	v_cmp_neq_f32_e32 vcc, s46, v6
	v_mul_f32_e32 v11, v10, v9
	v_mul_f32_e32 v12, v7, v11
	v_fma_f32 v13, v11, v7, -v12
	v_fmac_f32_e32 v13, v11, v3
	v_add_f32_e32 v14, v12, v13
	v_sub_f32_e32 v15, v10, v14
	v_sub_f32_e32 v10, v10, v15
	v_sub_f32_e32 v12, v14, v12
	v_sub_f32_e32 v10, v10, v14
	v_add_f32_e32 v8, v8, v10
; __device__ __forceinline__ float log_sigmoid(float x) { return fminf(x, 0.f) - log1pf(expf(-fabsf(x))); }
; __device__ __forceinline__ void ret_contrib_unit(int unit, int next_unit, RetKV& pre, const bf16* RK, const bf16* RV, const float* decay_l, float* RETC, lds_t* lds, int tid, int lane, int wave) {
;     ...
;     { const int j = tid >> 2, d0 = (tid & 3) * 16; const float wf = __expf(lgf * (float)(127 - j)), wb = __expf(lgb * (float)j);
	v_sub_f32_e32 v10, v12, v13
	v_add_f32_e32 v8, v10, v8
	v_add_f32_e32 v10, v15, v8
	v_mul_f32_e32 v12, v9, v10
	v_mul_f32_e32 v13, v7, v12
	v_fma_f32 v7, v12, v7, -v13
	v_fmac_f32_e32 v7, v12, v3
	v_sub_f32_e32 v3, v15, v10
	v_add_f32_e32 v3, v8, v3
	v_add_f32_e32 v8, v13, v7
	v_sub_f32_e32 v14, v10, v8
	v_sub_f32_e32 v10, v10, v14
	v_sub_f32_e32 v13, v8, v13
	v_sub_f32_e32 v8, v10, v8
	v_add_f32_e32 v3, v3, v8
	v_sub_f32_e32 v7, v13, v7
	v_add_f32_e32 v3, v7, v3
	v_add_f32_e32 v7, v11, v12
	v_add_f32_e32 v3, v14, v3
	v_sub_f32_e32 v8, v7, v11
	v_mul_f32_e32 v3, v9, v3
	v_sub_f32_e32 v8, v12, v8
	v_add_f32_e32 v3, v8, v3
	v_mul_f32_e32 v11, 0x3f317218, v2
	v_add_f32_e32 v8, v7, v3
	v_fma_f32 v12, v2, s49, -v11
	v_mul_f32_e32 v9, v8, v8
	v_fmac_f32_e32 v12, 0xb102e308, v2
	v_sub_f32_e32 v2, v8, v7
	v_fmamk_f32 v10, v9, 0x3e9b6dac, v217
	v_sub_f32_e32 v2, v3, v2
	v_add_f32_e32 v3, v11, v12
	v_fmaak_f32 v10, v9, v10, 0x3f2aaada
	v_sub_f32_e32 v7, v3, v11
	v_ldexp_f32 v11, v8, 1
	v_mul_f32_e32 v8, v8, v9
	v_mul_f32_e32 v8, v8, v10
	v_add_f32_e32 v9, v11, v8
	v_sub_f32_e32 v10, v9, v11
	v_ldexp_f32 v2, v2, 1
	v_sub_f32_e32 v8, v8, v10
	v_add_f32_e32 v2, v2, v8
	v_add_f32_e32 v8, v9, v2
	v_sub_f32_e32 v9, v8, v9
	v_sub_f32_e32 v2, v2, v9
	v_add_f32_e32 v9, v3, v8
	v_sub_f32_e32 v10, v9, v3
	v_sub_f32_e32 v11, v9, v10
	v_sub_f32_e32 v7, v12, v7
	v_sub_f32_e32 v3, v3, v11
	v_sub_f32_e32 v8, v8, v10
	v_add_f32_e32 v3, v8, v3
	v_add_f32_e32 v8, v7, v2
	v_sub_f32_e32 v10, v8, v7
	v_sub_f32_e32 v11, v8, v10
	v_sub_f32_e32 v7, v7, v11
	v_sub_f32_e32 v2, v2, v10
	v_add_f32_e32 v3, v8, v3
	v_add_f32_e32 v2, v2, v7
	v_add_f32_e32 v7, v9, v3
	v_sub_f32_e32 v8, v7, v9
	v_sub_f32_e32 v3, v3, v8
	v_add_f32_e32 v2, v2, v3
	v_mul_f32_e32 v3, v4, v30
	v_add_f32_e32 v2, v7, v2
	v_mul_f32_e32 v3, 0x3fb8aa3b, v3
	v_cndmask_b32_e32 v2, v219, v2, vcc
	v_cmp_lt_f32_e64 vcc, |v6|, s50
	v_exp_f32_e32 v3, v3
	s_waitcnt vmcnt(16)
; #define LAS __attribute__((address_space(3)))
; __device__ __forceinline__ unsigned f2bf(float f) { unsigned u = __builtin_bit_cast(unsigned, f); return (u + 0x7fffu + ((u >> 16) & 1u)) >> 16; }
; __device__ __forceinline__ void ret_contrib_unit(int unit, int next_unit, RetKV& pre, const bf16* RK, const bf16* RV, const float* decay_l, float* RETC, lds_t* lds, int tid, int lane, int wave) {
;     ...
;     { const int j = tid >> 2, d0 = (tid & 3) * 16; const float wf = __expf(lgf * (float)(127 - j)), wb = __expf(lgb * (float)j);
; #pragma unroll
;         for (int q = 0; q < 2; ++q) { const v4u kw = pre.k[q], vw = pre.v[q];
; #pragma unroll
;             for (int e = 0; e < 4; ++e) { const unsigned kk = kw[e], vv = vw[e]; const int d = d0 + q * 8 + 2 * e; const float k0 = bflo(kk), k1 = bfhi(kk);
;                 *(LAS unsigned short*)(Kft + d * RT_LDK + j * 2) = (unsigned short)f2bf(k0 * wf); *(LAS unsigned short*)(Kft + (d + 1) * RT_LDK + j * 2) = (unsigned short)f2bf(k1 * wf);
;                 *(LAS unsigned short*)(Kbt + d * RT_LDK + j * 2) = (unsigned short)f2bf(k0 * wb); *(LAS unsigned short*)(Kbt + (d + 1) * RT_LDK + j * 2) = (unsigned short)f2bf(k1 * wb);
;                 *(LAS unsigned short*)(Vt + d * RT_LDK + j * 2) = (unsigned short)(vv & 0xffffu); *(LAS unsigned short*)(Vt + (d + 1) * RT_LDK + j * 2) = (unsigned short)(vv >> 16); } } }
;     __syncthreads();
;     if (next_unit >= 0) ret_contrib_load(pre, next_unit, RK, RV, tid);
	v_lshlrev_b32_e32 v4, 16, v118
	v_cndmask_b32_e32 v2, v2, v6, vcc
	v_sub_f32_e32 v2, v5, v2
	v_mul_f32_e32 v2, v2, v31
	v_mul_f32_e32 v2, 0x3fb8aa3b, v2
	v_mul_f32_e32 v6, v3, v4
	v_exp_f32_e32 v2, v2
	v_bfe_u32 v7, v6, 16, 1
	v_and_b32_e32 v5, 0xffff0000, v118
	v_add3_u32 v6, v6, v7, s33
	ds_write_b16_d16_hi v32, v6
	v_mul_f32_e32 v6, v3, v5
	v_bfe_u32 v7, v6, 16, 1
	v_add3_u32 v6, v6, v7, s33
	v_mul_f32_e32 v4, v2, v4
	ds_write_b16_d16_hi v32, v6 offset:272
	v_bfe_u32 v6, v4, 16, 1
	v_add3_u32 v4, v4, v6, s33
	ds_write_b16_d16_hi v32, v4 offset:17408
	v_mul_f32_e32 v4, v2, v5
	v_bfe_u32 v5, v4, 16, 1
	v_add3_u32 v4, v4, v5, s33
	ds_write_b16_d16_hi v32, v4 offset:17680
	ds_write_b16 v32, v122 offset:34816
	ds_write_b16_d16_hi v32, v122 offset:35088
	v_lshlrev_b32_e32 v4, 16, v119
	v_mul_f32_e32 v6, v3, v4
	v_bfe_u32 v7, v6, 16, 1
	v_and_b32_e32 v5, 0xffff0000, v119
	v_add3_u32 v6, v6, v7, s33
	ds_write_b16_d16_hi v32, v6 offset:544
	v_mul_f32_e32 v6, v3, v5
	v_bfe_u32 v7, v6, 16, 1
	v_add3_u32 v6, v6, v7, s33
	v_mul_f32_e32 v4, v2, v4
	ds_write_b16_d16_hi v32, v6 offset:816
	v_bfe_u32 v6, v4, 16, 1
	v_add3_u32 v4, v4, v6, s33
	ds_write_b16_d16_hi v32, v4 offset:17952
	v_mul_f32_e32 v4, v2, v5
	v_bfe_u32 v5, v4, 16, 1
	v_add3_u32 v4, v4, v5, s33
	ds_write_b16_d16_hi v32, v4 offset:18224
	ds_write_b16 v32, v123 offset:35360
	ds_write_b16_d16_hi v32, v123 offset:35632
	v_lshlrev_b32_e32 v4, 16, v120
	v_mul_f32_e32 v6, v3, v4
	v_bfe_u32 v7, v6, 16, 1
	v_and_b32_e32 v5, 0xffff0000, v120
	v_add3_u32 v6, v6, v7, s33
	ds_write_b16_d16_hi v32, v6 offset:1088
	v_mul_f32_e32 v6, v3, v5
	v_bfe_u32 v7, v6, 16, 1
	v_add3_u32 v6, v6, v7, s33
	v_mul_f32_e32 v4, v2, v4
	ds_write_b16_d16_hi v32, v6 offset:1360
	v_bfe_u32 v6, v4, 16, 1
	v_add3_u32 v4, v4, v6, s33
	ds_write_b16_d16_hi v32, v4 offset:18496
	v_mul_f32_e32 v4, v2, v5
	v_bfe_u32 v5, v4, 16, 1
	v_add3_u32 v4, v4, v5, s33
	ds_write_b16_d16_hi v32, v4 offset:18768
	ds_write_b16 v32, v124 offset:35904
	ds_write_b16_d16_hi v32, v124 offset:36176
	v_lshlrev_b32_e32 v4, 16, v121
	v_mul_f32_e32 v6, v3, v4
	v_bfe_u32 v7, v6, 16, 1
	v_and_b32_e32 v5, 0xffff0000, v121
	v_add3_u32 v6, v6, v7, s33
	ds_write_b16_d16_hi v32, v6 offset:1632
	v_mul_f32_e32 v6, v3, v5
	v_bfe_u32 v7, v6, 16, 1
	v_add3_u32 v6, v6, v7, s33
	v_mul_f32_e32 v4, v2, v4
	ds_write_b16_d16_hi v32, v6 offset:1904
	v_bfe_u32 v6, v4, 16, 1
	v_add3_u32 v4, v4, v6, s33
	ds_write_b16_d16_hi v32, v4 offset:19040
	v_mul_f32_e32 v4, v2, v5
	v_bfe_u32 v5, v4, 16, 1
	v_add3_u32 v4, v4, v5, s33
	ds_write_b16_d16_hi v32, v4 offset:19312
	ds_write_b16 v32, v125 offset:36448
	ds_write_b16_d16_hi v32, v125 offset:36720
	v_lshlrev_b32_e32 v4, 16, v114
	v_mul_f32_e32 v6, v3, v4
	v_bfe_u32 v7, v6, 16, 1
	v_and_b32_e32 v5, 0xffff0000, v114
	v_add3_u32 v6, v6, v7, s33
	ds_write_b16_d16_hi v32, v6 offset:2176
	v_mul_f32_e32 v6, v3, v5
	v_bfe_u32 v7, v6, 16, 1
	v_add3_u32 v6, v6, v7, s33
	v_mul_f32_e32 v4, v2, v4
	ds_write_b16_d16_hi v32, v6 offset:2448
	v_bfe_u32 v6, v4, 16, 1
	v_add3_u32 v4, v4, v6, s33
	ds_write_b16_d16_hi v32, v4 offset:19584
	v_mul_f32_e32 v4, v2, v5
	v_bfe_u32 v5, v4, 16, 1
	v_add3_u32 v4, v4, v5, s33
	ds_write_b16_d16_hi v32, v4 offset:19856
	ds_write_b16 v32, v126 offset:36992
	ds_write_b16_d16_hi v32, v126 offset:37264
	v_lshlrev_b32_e32 v4, 16, v115
	v_mul_f32_e32 v6, v3, v4
	v_bfe_u32 v7, v6, 16, 1
	v_and_b32_e32 v5, 0xffff0000, v115
	v_add3_u32 v6, v6, v7, s33
	ds_write_b16_d16_hi v32, v6 offset:2720
	v_mul_f32_e32 v6, v3, v5
	v_bfe_u32 v7, v6, 16, 1
	v_add3_u32 v6, v6, v7, s33
	v_mul_f32_e32 v4, v2, v4
	ds_write_b16_d16_hi v32, v6 offset:2992
	v_bfe_u32 v6, v4, 16, 1
	v_add3_u32 v4, v4, v6, s33
	ds_write_b16_d16_hi v32, v4 offset:20128
	v_mul_f32_e32 v4, v2, v5
	v_bfe_u32 v5, v4, 16, 1
	v_add3_u32 v4, v4, v5, s33
	ds_write_b16_d16_hi v32, v4 offset:20400
	ds_write_b16 v32, v127 offset:37536
	ds_write_b16_d16_hi v32, v127 offset:37808
	v_lshlrev_b32_e32 v4, 16, v116
	v_mul_f32_e32 v6, v3, v4
	v_bfe_u32 v7, v6, 16, 1
	v_and_b32_e32 v5, 0xffff0000, v116
	v_add3_u32 v6, v6, v7, s33
	ds_write_b16_d16_hi v32, v6 offset:3264
	v_mul_f32_e32 v6, v3, v5
	v_bfe_u32 v7, v6, 16, 1
	v_add3_u32 v6, v6, v7, s33
	v_mul_f32_e32 v4, v2, v4
	ds_write_b16_d16_hi v32, v6 offset:3536
	v_bfe_u32 v6, v4, 16, 1
	v_add3_u32 v4, v4, v6, s33
	ds_write_b16_d16_hi v32, v4 offset:20672
	v_mul_f32_e32 v4, v2, v5
	v_bfe_u32 v5, v4, 16, 1
	v_add3_u32 v4, v4, v5, s33
	ds_write_b16_d16_hi v32, v4 offset:20944
	ds_write_b16 v32, v128 offset:38080
	ds_write_b16_d16_hi v32, v128 offset:38352
	v_lshlrev_b32_e32 v4, 16, v117
	v_mul_f32_e32 v6, v3, v4
	v_and_b32_e32 v5, 0xffff0000, v117
	v_bfe_u32 v7, v6, 16, 1
	v_add3_u32 v6, v6, v7, s33
	v_mul_f32_e32 v3, v3, v5
	ds_write_b16_d16_hi v32, v6 offset:3808
	v_bfe_u32 v6, v3, 16, 1
	v_add3_u32 v3, v3, v6, s33
	ds_write_b16_d16_hi v32, v3 offset:4080
	v_mul_f32_e32 v3, v2, v4
	v_bfe_u32 v4, v3, 16, 1
	v_add3_u32 v3, v3, v4, s33
	v_mul_f32_e32 v2, v2, v5
	ds_write_b16_d16_hi v32, v3 offset:21216
	v_bfe_u32 v3, v2, 16, 1
	v_add3_u32 v2, v2, v3, s33
	ds_write_b16_d16_hi v32, v2 offset:21488
	ds_write_b16 v32, v129 offset:38624
	ds_write_b16_d16_hi v32, v129 offset:38896
	s_waitcnt lgkmcnt(0)
	s_barrier
	s_cbranch_scc1 .LBB0_543
	s_mul_hi_u32 s12, s1, 0xf0f0f0f1
	s_lshr_b32 s7, s12, 5
	s_mul_i32 s13, s7, 34
	s_sub_i32 s13, s1, s13
	s_lshr_b32 s1, s12, 7
	s_lshl_b32 s15, s13, 7
	s_cmp_gt_u32 s13, 31
	s_mov_b64 s[12:13], -1
	s_cbranch_scc0 .LBB0_547
	s_lshl_b32 s12, s1, 8
	s_add_i32 s12, s15, s12
	s_add_i32 s16, s12, 0x7000
	s_mov_b64 s[12:13], 0
